# attention QK^T: two K-fragment ds_reads kept in flight (distance-2 pipeline)
# speedup vs baseline: 1.0080x; 1.0080x over previous
; template <int D0> __device__ __forceinline__ void pv_one(f32x16& od, int vb, bf16x8 pa0, bf16x8 pa1, bf16x8 pa2, bf16x8 pa3) {
;   const s16x4 l0 = tr_read<v_rd_off(D0, 0, 0)>(vb), h0 = tr_read<v_rd_off(D0, 0, 1)>(vb), l1 = tr_read<v_rd_off(D0, 1, 0)>(vb), h1 = tr_read<v_rd_off(D0, 1, 1)>(vb);
;   const s16x4 l2 = tr_read<v_rd_off(D0, 2, 0)>(vb), h2 = tr_read<v_rd_off(D0, 2, 1)>(vb), l3 = tr_read<v_rd_off(D0, 3, 0)>(vb), h3 = tr_read<v_rd_off(D0, 3, 1)>(vb);
;   asm volatile("s_waitcnt lgkmcnt(0)" ::: "memory"); SBAR();
;     ...
;   od = __builtin_amdgcn_mfma_f32_32x32x16_bf16(pa0, PK(l0, h0), od, 0, 0, 0);
;   od = __builtin_amdgcn_mfma_f32_32x32x16_bf16(pa1, PK(l1, h1), od, 0, 0, 0);
;   od = __builtin_amdgcn_mfma_f32_32x32x16_bf16(pa2, PK(l2, h2), od, 0, 0, 0);
;   od = __builtin_amdgcn_mfma_f32_32x32x16_bf16(pa3, PK(l3, h3), od, 0, 0, 0);
;     ...
; }
; __device__ __forceinline__ void pv_d0(f32x16* o, int vb, bf16x8 pa0, bf16x8 pa1, bf16x8 pa2, bf16x8 pa3) {
;   pv_one<0>(o[0], vb, pa0, pa1, pa2, pa3); pv_one<1>(o[1], vb, pa0, pa1, pa2, pa3); pv_one<2>(o[2], vb, pa0, pa1, pa2, pa3); pv_one<3>(o[3], vb, pa0, pa1, pa2, pa3);
; }
; __device__ __forceinline__ void qkt_c(f32x16& p0, f32x16& p1, const char* Ks, const bf16x8* qr, const f32x16& negm, int r32, int hi) {
; #pragma unroll
;   for (int d0 = 0; d0 < 4; ++d0) { const int cb = (d0 * 16 + hi * 8) * 2;
;     bf16x8 b0 = *reinterpret_cast<const bf16x8*>(Ks + KSWZ(r32, cb));
;     bf16x8 b1 = *reinterpret_cast<const bf16x8*>(Ks + KSWZ(32 + r32, cb));
;     if (d0 == 0) { p0 = __builtin_amdgcn_mfma_f32_32x32x16_bf16(b0, qr[0], negm, 0, 0, 0); p1 = __builtin_amdgcn_mfma_f32_32x32x16_bf16(b1, qr[0], negm, 0, 0, 0); }
;     else { p0 = __builtin_amdgcn_mfma_f32_32x32x16_bf16(b0, qr[d0], p0, 0, 0, 0); p1 = __builtin_amdgcn_mfma_f32_32x32x16_bf16(b1, qr[d0], p1, 0, 0, 0); } }
; }
; template <int R> __device__ __forceinline__ void bias_r(f32x16& p0, f32x16& p1, float dq, float nslope) {
;   constexpr int C0 = (R & 3) + 8 * (R >> 2);
;   float x0, x1, a0 = p0[R], a1 = p1[R];
;   asm("v_sub_f32_e32 %0, %1, %2" : "=v"(x0) : "n"(__builtin_bit_cast(int, (float)C0)), "v"(dq));
;   asm("v_sub_f32_e32 %0, %1, %2" : "=v"(x1) : "n"(__builtin_bit_cast(int, (float)(C0 + 32))), "v"(dq));
;   asm("v_fma_f32 %0, %1, |%2|, %0" : "+v"(a0) : "v"(nslope), "v"(x0));
;   asm("v_fma_f32 %0, %1, |%2|, %0" : "+v"(a1) : "v"(nslope), "v"(x1));
.LBB0_364:
	ds_read_b128 v[114:117], v195 offset:32768
	ds_read_b128 v[204:207], v195 offset:40960
	ds_read_b128 v[208:211], v196 offset:32768
	s_and_b64 vcc, exec, s[14:15]
	s_waitcnt lgkmcnt(2)
	v_mfma_f32_32x32x16_bf16 v[98:113], v[114:117], v[130:133], v[82:97]
	ds_read_b128 v[212:215], v196 offset:40960
	s_waitcnt lgkmcnt(2)
	v_mfma_f32_32x32x16_bf16 v[114:129], v[204:207], v[130:133], v[82:97]
	ds_read_b128 v[204:207], v197 offset:32768
	s_waitcnt lgkmcnt(2)
	v_mfma_f32_32x32x16_bf16 v[98:113], v[208:211], v[134:137], v[98:113]
	ds_read_b128 v[208:211], v197 offset:40960
	s_waitcnt lgkmcnt(2)
	v_mfma_f32_32x32x16_bf16 v[114:129], v[212:215], v[134:137], v[114:129]
	ds_read_b128 v[212:215], v198 offset:32768
	s_waitcnt lgkmcnt(2)
	v_mfma_f32_32x32x16_bf16 v[98:113], v[204:207], v[138:141], v[98:113]
	ds_read_b128 v[204:207], v198 offset:40960
	s_waitcnt lgkmcnt(2)
	v_mfma_f32_32x32x16_bf16 v[114:129], v[208:211], v[138:141], v[114:129]
	s_waitcnt lgkmcnt(1)
	v_mfma_f32_32x32x16_bf16 v[98:113], v[212:215], v[142:145], v[98:113]
	s_waitcnt lgkmcnt(0)
	v_mfma_f32_32x32x16_bf16 v[114:129], v[204:207], v[142:145], v[114:129]
	s_cbranch_vccnz .LBB0_366
	s_add_i32 s72, s22, s46
	s_cmp_lt_i32 s46, s23
	s_cselect_b32 s14, s72, s39
	s_lshl_b32 s14, s14, 6
	v_cvt_f32_i32_e32 v0, s14
	v_sub_f32_e32 v0, v192, v0
	ds_read_b64_tr_b16 v[204:205], v194 offset:0
	ds_read_b64_tr_b16 v[206:207], v194 offset:0x800
	ds_read_b64_tr_b16 v[208:209], v194 offset:0x1000
	ds_read_b64_tr_b16 v[210:211], v194 offset:0x1800
	ds_read_b64_tr_b16 v[212:213], v194 offset:0x2000
	ds_read_b64_tr_b16 v[214:215], v194 offset:0x2800
	ds_read_b64_tr_b16 v[216:217], v194 offset:0x3000
	ds_read_b64_tr_b16 v[218:219], v194 offset:0x3800
	s_waitcnt lgkmcnt(0)
	s_nop 0
	v_mfma_f32_32x32x16_bf16 v[64:79], v[2:5], v[204:207], v[64:79]
	v_sub_f32_e32 v14, 0, v0
	v_sub_f32_e32 v15, 0x42000000, v0
	v_fma_f32 v98, v81, |v14|, v98
	v_sub_f32_e32 v14, 0x3f800000, v0
	ds_read_b64_tr_b16 v[204:205], v194 offset:0x200
	ds_read_b64_tr_b16 v[206:207], v194 offset:0xa00
	v_mfma_f32_32x32x16_bf16 v[64:79], v[6:9], v[208:211], v[64:79]
	v_fma_f32 v114, v81, |v15|, v114
	v_sub_f32_e32 v15, 0x42040000, v0
	v_fma_f32 v99, v81, |v14|, v99
	v_sub_f32_e32 v14, 0x40000000, v0
	ds_read_b64_tr_b16 v[208:209], v194 offset:0x1200
	ds_read_b64_tr_b16 v[210:211], v194 offset:0x1a00
	v_mfma_f32_32x32x16_bf16 v[64:79], v[10:13], v[212:215], v[64:79]
	v_fma_f32 v115, v81, |v15|, v115
	v_sub_f32_e32 v15, 0x42080000, v0
	v_fma_f32 v100, v81, |v14|, v100
	v_sub_f32_e32 v14, 0x40400000, v0
	ds_read_b64_tr_b16 v[212:213], v194 offset:0x2200
	ds_read_b64_tr_b16 v[214:215], v194 offset:0x2a00
	ds_read_b64_tr_b16 v[220:221], v194 offset:0x3200
	ds_read_b64_tr_b16 v[222:223], v194 offset:0x3a00
	s_waitcnt lgkmcnt(0)
	v_mfma_f32_32x32x16_bf16 v[64:79], v[162:165], v[216:219], v[64:79]
	v_fma_f32 v116, v81, |v15|, v116
	v_sub_f32_e32 v15, 0x420c0000, v0
	v_fma_f32 v101, v81, |v14|, v101
	v_sub_f32_e32 v14, 0x41000000, v0
	v_mfma_f32_32x32x16_bf16 v[48:63], v[2:5], v[204:207], v[48:63]
	v_fma_f32 v117, v81, |v15|, v117
	v_sub_f32_e32 v15, 0x42200000, v0
	v_fma_f32 v102, v81, |v14|, v102
	v_sub_f32_e32 v14, 0x41100000, v0
	ds_read_b64_tr_b16 v[204:205], v194 offset:0x400
	ds_read_b64_tr_b16 v[206:207], v194 offset:0xc00
	v_mfma_f32_32x32x16_bf16 v[48:63], v[6:9], v[208:211], v[48:63]
	v_fma_f32 v118, v81, |v15|, v118
	v_sub_f32_e32 v15, 0x42240000, v0
	v_fma_f32 v103, v81, |v14|, v103
	v_sub_f32_e32 v14, 0x41200000, v0
	ds_read_b64_tr_b16 v[208:209], v194 offset:0x1400
	ds_read_b64_tr_b16 v[210:211], v194 offset:0x1c00
	v_mfma_f32_32x32x16_bf16 v[48:63], v[10:13], v[212:215], v[48:63]
	v_fma_f32 v119, v81, |v15|, v119
	v_sub_f32_e32 v15, 0x42280000, v0
	v_fma_f32 v104, v81, |v14|, v104
	v_sub_f32_e32 v14, 0x41300000, v0
	ds_read_b64_tr_b16 v[212:213], v194 offset:0x2400
	ds_read_b64_tr_b16 v[214:215], v194 offset:0x2c00
	ds_read_b64_tr_b16 v[216:217], v194 offset:0x3400
	ds_read_b64_tr_b16 v[218:219], v194 offset:0x3c00
	s_waitcnt lgkmcnt(0)
	v_mfma_f32_32x32x16_bf16 v[48:63], v[162:165], v[220:223], v[48:63]
	v_fma_f32 v120, v81, |v15|, v120
	v_sub_f32_e32 v15, 0x422c0000, v0
	v_fma_f32 v105, v81, |v14|, v105
	v_sub_f32_e32 v14, 0x41800000, v0
	v_mfma_f32_32x32x16_bf16 v[32:47], v[2:5], v[204:207], v[32:47]
	v_fma_f32 v121, v81, |v15|, v121
	v_sub_f32_e32 v15, 0x42400000, v0
	v_fma_f32 v106, v81, |v14|, v106
	v_sub_f32_e32 v14, 0x41880000, v0
	ds_read_b64_tr_b16 v[204:205], v194 offset:0x600
	ds_read_b64_tr_b16 v[206:207], v194 offset:0xe00
	v_mfma_f32_32x32x16_bf16 v[32:47], v[6:9], v[208:211], v[32:47]
	v_fma_f32 v122, v81, |v15|, v122
	v_sub_f32_e32 v15, 0x42440000, v0
	v_fma_f32 v107, v81, |v14|, v107
	v_sub_f32_e32 v14, 0x41900000, v0
	ds_read_b64_tr_b16 v[208:209], v194 offset:0x1600
	ds_read_b64_tr_b16 v[210:211], v194 offset:0x1e00
	v_mfma_f32_32x32x16_bf16 v[32:47], v[10:13], v[212:215], v[32:47]
	v_fma_f32 v123, v81, |v15|, v123
	v_sub_f32_e32 v15, 0x42480000, v0
	v_fma_f32 v108, v81, |v14|, v108
	v_sub_f32_e32 v14, 0x41980000, v0
	ds_read_b64_tr_b16 v[212:213], v194 offset:0x2600
	ds_read_b64_tr_b16 v[214:215], v194 offset:0x2e00
	ds_read_b64_tr_b16 v[220:221], v194 offset:0x3600
	ds_read_b64_tr_b16 v[222:223], v194 offset:0x3e00
	s_waitcnt lgkmcnt(0)
	v_mfma_f32_32x32x16_bf16 v[32:47], v[162:165], v[216:219], v[32:47]
	v_fma_f32 v124, v81, |v15|, v124
	v_sub_f32_e32 v15, 0x424c0000, v0
	v_fma_f32 v109, v81, |v14|, v109
	v_sub_f32_e32 v14, 0x41c00000, v0
	v_mfma_f32_32x32x16_bf16 v[16:31], v[2:5], v[204:207], v[16:31]
	v_fma_f32 v125, v81, |v15|, v125
	v_sub_f32_e32 v15, 0x42600000, v0
	v_fma_f32 v110, v81, |v14|, v110
	v_sub_f32_e32 v14, 0x41c80000, v0
	v_mfma_f32_32x32x16_bf16 v[16:31], v[6:9], v[208:211], v[16:31]
	v_fma_f32 v126, v81, |v15|, v126
	v_sub_f32_e32 v15, 0x42640000, v0
	v_fma_f32 v111, v81, |v14|, v111
	v_sub_f32_e32 v14, 0x41d00000, v0
	v_mfma_f32_32x32x16_bf16 v[16:31], v[10:13], v[212:215], v[16:31]
	v_fma_f32 v127, v81, |v15|, v127
	v_sub_f32_e32 v15, 0x42680000, v0
	v_fma_f32 v112, v81, |v14|, v112
	v_sub_f32_e32 v14, 0x41d80000, v0
	v_mfma_f32_32x32x16_bf16 v[16:31], v[162:165], v[220:223], v[16:31]
	v_sub_f32_e32 v0, 0x426c0000, v0
	v_fma_f32 v128, v81, |v15|, v128
	v_fma_f32 v113, v81, |v14|, v113
	v_fma_f32 v129, v81, |v0|, v129
	s_barrier
	s_branch .Lafter_bias_0

; template <int D0> __device__ __forceinline__ void pv_one(f32x16& od, int vb, bf16x8 pa0, bf16x8 pa1, bf16x8 pa2, bf16x8 pa3) {
;   const s16x4 l0 = tr_read<v_rd_off(D0, 0, 0)>(vb), h0 = tr_read<v_rd_off(D0, 0, 1)>(vb), l1 = tr_read<v_rd_off(D0, 1, 0)>(vb), h1 = tr_read<v_rd_off(D0, 1, 1)>(vb);
;   const s16x4 l2 = tr_read<v_rd_off(D0, 2, 0)>(vb), h2 = tr_read<v_rd_off(D0, 2, 1)>(vb), l3 = tr_read<v_rd_off(D0, 3, 0)>(vb), h3 = tr_read<v_rd_off(D0, 3, 1)>(vb);
;   asm volatile("s_waitcnt lgkmcnt(0)" ::: "memory"); SBAR();
;     ...
;   od = __builtin_amdgcn_mfma_f32_32x32x16_bf16(pa0, PK(l0, h0), od, 0, 0, 0);
;   od = __builtin_amdgcn_mfma_f32_32x32x16_bf16(pa1, PK(l1, h1), od, 0, 0, 0);
;   od = __builtin_amdgcn_mfma_f32_32x32x16_bf16(pa2, PK(l2, h2), od, 0, 0, 0);
;   od = __builtin_amdgcn_mfma_f32_32x32x16_bf16(pa3, PK(l3, h3), od, 0, 0, 0);
;     ...
; }
; __device__ __forceinline__ void pv_d0(f32x16* o, int vb, bf16x8 pa0, bf16x8 pa1, bf16x8 pa2, bf16x8 pa3) {
;   pv_one<0>(o[0], vb, pa0, pa1, pa2, pa3); pv_one<1>(o[1], vb, pa0, pa1, pa2, pa3); pv_one<2>(o[2], vb, pa0, pa1, pa2, pa3); pv_one<3>(o[3], vb, pa0, pa1, pa2, pa3);
; }
; __device__ __forceinline__ void qkt_c(f32x16& p0, f32x16& p1, const char* Ks, const bf16x8* qr, const f32x16& negm, int r32, int hi) {
; #pragma unroll
;   for (int d0 = 0; d0 < 4; ++d0) { const int cb = (d0 * 16 + hi * 8) * 2;
;     bf16x8 b0 = *reinterpret_cast<const bf16x8*>(Ks + KSWZ(r32, cb));
;     bf16x8 b1 = *reinterpret_cast<const bf16x8*>(Ks + KSWZ(32 + r32, cb));
;     if (d0 == 0) { p0 = __builtin_amdgcn_mfma_f32_32x32x16_bf16(b0, qr[0], negm, 0, 0, 0); p1 = __builtin_amdgcn_mfma_f32_32x32x16_bf16(b1, qr[0], negm, 0, 0, 0); }
;     else { p0 = __builtin_amdgcn_mfma_f32_32x32x16_bf16(b0, qr[d0], p0, 0, 0, 0); p1 = __builtin_amdgcn_mfma_f32_32x32x16_bf16(b1, qr[d0], p1, 0, 0, 0); } }
; }
; template <int R> __device__ __forceinline__ void bias_r(f32x16& p0, f32x16& p1, float dq, float nslope) {
;   constexpr int C0 = (R & 3) + 8 * (R >> 2);
;   float x0, x1, a0 = p0[R], a1 = p1[R];
;   asm("v_sub_f32_e32 %0, %1, %2" : "=v"(x0) : "n"(__builtin_bit_cast(int, (float)C0)), "v"(dq));
;   asm("v_sub_f32_e32 %0, %1, %2" : "=v"(x1) : "n"(__builtin_bit_cast(int, (float)(C0 + 32))), "v"(dq));
;   asm("v_fma_f32 %0, %1, |%2|, %0" : "+v"(a0) : "v"(nslope), "v"(x0));
;   asm("v_fma_f32 %0, %1, |%2|, %0" : "+v"(a1) : "v"(nslope), "v"(x1));
.LBB0_379:
	s_waitcnt lgkmcnt(0)
	s_barrier
	ds_read_b128 v[114:117], v195 offset:49152
	ds_read_b128 v[204:207], v195 offset:57344
	ds_read_b128 v[208:211], v196 offset:49152
	s_andn2_b64 vcc, exec, s[14:15]
	s_waitcnt lgkmcnt(2)
	v_mfma_f32_32x32x16_bf16 v[98:113], v[114:117], v[130:133], v[82:97]
	ds_read_b128 v[212:215], v196 offset:57344
	s_waitcnt lgkmcnt(2)
	v_mfma_f32_32x32x16_bf16 v[114:129], v[204:207], v[130:133], v[82:97]
	ds_read_b128 v[204:207], v197 offset:49152
	s_waitcnt lgkmcnt(2)
	v_mfma_f32_32x32x16_bf16 v[98:113], v[208:211], v[134:137], v[98:113]
	ds_read_b128 v[208:211], v197 offset:57344
	s_waitcnt lgkmcnt(2)
	v_mfma_f32_32x32x16_bf16 v[114:129], v[212:215], v[134:137], v[114:129]
	ds_read_b128 v[212:215], v198 offset:49152
	s_waitcnt lgkmcnt(2)
	v_mfma_f32_32x32x16_bf16 v[98:113], v[204:207], v[138:141], v[98:113]
	ds_read_b128 v[204:207], v198 offset:57344
	s_waitcnt lgkmcnt(2)
	v_mfma_f32_32x32x16_bf16 v[114:129], v[208:211], v[138:141], v[114:129]
	s_waitcnt lgkmcnt(1)
	v_mfma_f32_32x32x16_bf16 v[98:113], v[212:215], v[142:145], v[98:113]
	s_waitcnt lgkmcnt(0)
	v_mfma_f32_32x32x16_bf16 v[114:129], v[204:207], v[142:145], v[114:129]
	s_cbranch_vccnz .LBB0_381
	s_add_i32 s46, s47, -1
	s_add_i32 s72, s72, 1
	s_add_i32 s14, s39, -1
	s_cmp_lt_i32 s46, s23
	s_cselect_b32 s14, s72, s14
	s_lshl_b32 s14, s14, 6
	v_cvt_f32_i32_e32 v0, s14
	v_sub_f32_e32 v0, v192, v0
	ds_read_b64_tr_b16 v[204:205], v193 offset:0
	ds_read_b64_tr_b16 v[206:207], v193 offset:0x800
	ds_read_b64_tr_b16 v[208:209], v193 offset:0x1000
	ds_read_b64_tr_b16 v[210:211], v193 offset:0x1800
	ds_read_b64_tr_b16 v[212:213], v193 offset:0x2000
	ds_read_b64_tr_b16 v[214:215], v193 offset:0x2800
	ds_read_b64_tr_b16 v[216:217], v193 offset:0x3000
	ds_read_b64_tr_b16 v[218:219], v193 offset:0x3800
	s_waitcnt lgkmcnt(0)
	s_nop 0
	v_mfma_f32_32x32x16_bf16 v[64:79], v[2:5], v[204:207], v[64:79]
	v_sub_f32_e32 v14, 0, v0
	v_sub_f32_e32 v15, 0x42000000, v0
	v_fma_f32 v98, v81, |v14|, v98
	v_sub_f32_e32 v14, 0x3f800000, v0
	ds_read_b64_tr_b16 v[204:205], v193 offset:0x200
	ds_read_b64_tr_b16 v[206:207], v193 offset:0xa00
	v_mfma_f32_32x32x16_bf16 v[64:79], v[6:9], v[208:211], v[64:79]
	v_fma_f32 v114, v81, |v15|, v114
	v_sub_f32_e32 v15, 0x42040000, v0
	v_fma_f32 v99, v81, |v14|, v99
	v_sub_f32_e32 v14, 0x40000000, v0
	ds_read_b64_tr_b16 v[208:209], v193 offset:0x1200
	ds_read_b64_tr_b16 v[210:211], v193 offset:0x1a00
	v_mfma_f32_32x32x16_bf16 v[64:79], v[10:13], v[212:215], v[64:79]
	v_fma_f32 v115, v81, |v15|, v115
	v_sub_f32_e32 v15, 0x42080000, v0
	v_fma_f32 v100, v81, |v14|, v100
	v_sub_f32_e32 v14, 0x40400000, v0
	ds_read_b64_tr_b16 v[212:213], v193 offset:0x2200
	ds_read_b64_tr_b16 v[214:215], v193 offset:0x2a00
	ds_read_b64_tr_b16 v[220:221], v193 offset:0x3200
	ds_read_b64_tr_b16 v[222:223], v193 offset:0x3a00
	s_waitcnt lgkmcnt(0)
	v_mfma_f32_32x32x16_bf16 v[64:79], v[162:165], v[216:219], v[64:79]
	v_fma_f32 v116, v81, |v15|, v116
	v_sub_f32_e32 v15, 0x420c0000, v0
	v_fma_f32 v101, v81, |v14|, v101
	v_sub_f32_e32 v14, 0x41000000, v0
	v_mfma_f32_32x32x16_bf16 v[48:63], v[2:5], v[204:207], v[48:63]
	v_fma_f32 v117, v81, |v15|, v117
	v_sub_f32_e32 v15, 0x42200000, v0
	v_fma_f32 v102, v81, |v14|, v102
	v_sub_f32_e32 v14, 0x41100000, v0
	ds_read_b64_tr_b16 v[204:205], v193 offset:0x400
	ds_read_b64_tr_b16 v[206:207], v193 offset:0xc00
	v_mfma_f32_32x32x16_bf16 v[48:63], v[6:9], v[208:211], v[48:63]
	v_fma_f32 v118, v81, |v15|, v118
	v_sub_f32_e32 v15, 0x42240000, v0
	v_fma_f32 v103, v81, |v14|, v103
	v_sub_f32_e32 v14, 0x41200000, v0
	ds_read_b64_tr_b16 v[208:209], v193 offset:0x1400
	ds_read_b64_tr_b16 v[210:211], v193 offset:0x1c00
	v_mfma_f32_32x32x16_bf16 v[48:63], v[10:13], v[212:215], v[48:63]
	v_fma_f32 v119, v81, |v15|, v119
	v_sub_f32_e32 v15, 0x42280000, v0
	v_fma_f32 v104, v81, |v14|, v104
	v_sub_f32_e32 v14, 0x41300000, v0
	ds_read_b64_tr_b16 v[212:213], v193 offset:0x2400
	ds_read_b64_tr_b16 v[214:215], v193 offset:0x2c00
	ds_read_b64_tr_b16 v[216:217], v193 offset:0x3400
	ds_read_b64_tr_b16 v[218:219], v193 offset:0x3c00
	s_waitcnt lgkmcnt(0)
	v_mfma_f32_32x32x16_bf16 v[48:63], v[162:165], v[220:223], v[48:63]
	v_fma_f32 v120, v81, |v15|, v120
	v_sub_f32_e32 v15, 0x422c0000, v0
	v_fma_f32 v105, v81, |v14|, v105
	v_sub_f32_e32 v14, 0x41800000, v0
	v_mfma_f32_32x32x16_bf16 v[32:47], v[2:5], v[204:207], v[32:47]
	v_fma_f32 v121, v81, |v15|, v121
	v_sub_f32_e32 v15, 0x42400000, v0
	v_fma_f32 v106, v81, |v14|, v106
	v_sub_f32_e32 v14, 0x41880000, v0
	ds_read_b64_tr_b16 v[204:205], v193 offset:0x600
	ds_read_b64_tr_b16 v[206:207], v193 offset:0xe00
	v_mfma_f32_32x32x16_bf16 v[32:47], v[6:9], v[208:211], v[32:47]
	v_fma_f32 v122, v81, |v15|, v122
	v_sub_f32_e32 v15, 0x42440000, v0
	v_fma_f32 v107, v81, |v14|, v107
	v_sub_f32_e32 v14, 0x41900000, v0
	ds_read_b64_tr_b16 v[208:209], v193 offset:0x1600
	ds_read_b64_tr_b16 v[210:211], v193 offset:0x1e00
	v_mfma_f32_32x32x16_bf16 v[32:47], v[10:13], v[212:215], v[32:47]
	v_fma_f32 v123, v81, |v15|, v123
	v_sub_f32_e32 v15, 0x42480000, v0
	v_fma_f32 v108, v81, |v14|, v108
	v_sub_f32_e32 v14, 0x41980000, v0
	ds_read_b64_tr_b16 v[212:213], v193 offset:0x2600
	ds_read_b64_tr_b16 v[214:215], v193 offset:0x2e00
	ds_read_b64_tr_b16 v[220:221], v193 offset:0x3600
	ds_read_b64_tr_b16 v[222:223], v193 offset:0x3e00
	s_waitcnt lgkmcnt(0)
	v_mfma_f32_32x32x16_bf16 v[32:47], v[162:165], v[216:219], v[32:47]
	v_fma_f32 v124, v81, |v15|, v124
	v_sub_f32_e32 v15, 0x424c0000, v0
	v_fma_f32 v109, v81, |v14|, v109
	v_sub_f32_e32 v14, 0x41c00000, v0
	v_mfma_f32_32x32x16_bf16 v[16:31], v[2:5], v[204:207], v[16:31]
	v_fma_f32 v125, v81, |v15|, v125
	v_sub_f32_e32 v15, 0x42600000, v0
	v_fma_f32 v110, v81, |v14|, v110
	v_sub_f32_e32 v14, 0x41c80000, v0
	v_mfma_f32_32x32x16_bf16 v[16:31], v[6:9], v[208:211], v[16:31]
	v_fma_f32 v126, v81, |v15|, v126
	v_sub_f32_e32 v15, 0x42640000, v0
	v_fma_f32 v111, v81, |v14|, v111
	v_sub_f32_e32 v14, 0x41d00000, v0
	v_mfma_f32_32x32x16_bf16 v[16:31], v[10:13], v[212:215], v[16:31]
	v_fma_f32 v127, v81, |v15|, v127
	v_sub_f32_e32 v15, 0x42680000, v0
	v_fma_f32 v112, v81, |v14|, v112
	v_sub_f32_e32 v14, 0x41d80000, v0
	v_mfma_f32_32x32x16_bf16 v[16:31], v[162:165], v[220:223], v[16:31]
	v_sub_f32_e32 v0, 0x426c0000, v0
	v_fma_f32 v128, v81, |v15|, v128
	v_fma_f32 v113, v81, |v14|, v113
	v_fma_f32 v129, v81, |v0|, v129
	s_barrier
	s_branch .Lafter_bias_1
